# attention units assigned statically and XCD-locally (first unit = xcd*16+slot, second = +128): no queue draws or id broadcast, adjacent query tiles share K/V in one XCD L2; replaces the dynamic queue
# speedup vs baseline: 1.0048x; 1.0048x over previous
; __device__ __forceinline__ void attn_issue(Frame& F, int id, KvRegs& R) {
;     const int b = id >> 5, n = (id >> 1) & 15, kvh = id & 1, key0 = 128 * (n - 1), tid = F.tid;
;     const bf16* Kb = (const bf16*)(F.ws + WS_K); const bf16* VT = (const bf16*)(F.ws + WS_VT);
;     const v4u zero4 = (v4u){0u, 0u, 0u, 0u};
; #pragma unroll
;     for (int i = 0; i < 6; ++i) { const int p = tid + 512 * i, row = p >> 3, pc = p & 7, pos = key0 + row;
;         R.k[i] = zero4; if (pos >= 0 && pos < SEQ) R.k[i] = *(const v4u*)(Kb + ((size_t)(b * SEQ + pos)) * 128 + kvh * 64 + pc * 8); }
; __device__ __forceinline__ void p2_mix(Frame& F, int slot) {
;     ...
;     if (F.tid == 0) F.MISC[16] = __hip_atomic_fetch_add(F.ctl + CW_ATTQ + 64 * F.dom, 1u, RLX_AGENT);
;     __syncthreads();
;     int id = (int)F.MISC[16];
;     __syncthreads();
;     if (id < NU) att::attn_issue(F, base + id, R);
.LBB0_513:
	v_cmp_eq_u32_e64 s[0:1], 0, v0
	s_waitcnt vmcnt(0) lgkmcnt(0)
	s_barrier
	s_lshl_b32 s33, s64, 4
	s_add_i32 s33, s33, s75
	v_mov_b32_e32 v1, s33
	s_lshl_b32 s11, s10, 8
	v_lshlrev_b32_e32 v8, 4, v0
	s_mov_b64 s[2:3], exec
	s_add_i32 s4, s33, s11
	s_ashr_i32 s14, s4, 5
	s_lshl_b32 s4, s4, 6
	s_and_b32 s16, s4, 0x780
	s_and_b32 s15, s4, 64
	s_addk_i32 s16, 0xff80
	s_lshl_b32 s17, s14, 11
	s_lshl_b32 s4, s15, 1
	s_add_u32 s4, s30, s4
	s_addc_u32 s5, s31, 0
	v_and_b32_e32 v114, 0x70, v8
	v_mov_b32_e32 v115, 0
	v_lshl_add_u64 v[2:3], s[4:5], 0, v[114:115]
	s_mov_b64 s[4:5], 0x9000000
	s_cmpk_gt_u32 s16, 0x7ff
	v_lshl_add_u64 v[2:3], v[2:3], 0, s[4:5]
	s_cbranch_scc1 .LBB0_521
	v_lshrrev_b32_e32 v1, 3, v0
	v_or_b32_e32 v1, s16, v1
	v_or_b32_e32 v4, s17, v1
	v_ashrrev_i32_e32 v5, 31, v4
	v_lshlrev_b64 v[4:5], 8, v[4:5]
	v_lshl_add_u64 v[4:5], v[2:3], 0, v[4:5]
	global_load_dwordx4 v[114:117], v[4:5], off
	s_branch .LBB0_522

; #define LAS __attribute__((address_space(3)))
; __device__ __forceinline__ void attn_commit(Frame& F, int id, const KvRegs& R) {
;     ...
;     for (int i = 0; i < 6; ++i) { const int p = tid + 512 * i, row = p >> 3, pc = p & 7; *(LAS v4u*)(lds + OFF_K + row * KROW + pc * 16) = R.k[i]; }
; #pragma unroll
;     for (int i = 0; i < 6; ++i) { const int p = tid + 512 * i, d = p / 48, pc = p - d * 48;
;         *(LAS v2u*)(lds + OFF_V + d * VROW + pc * 16) = (v2u){R.v[i].x, R.v[i].y}; *(LAS v2u*)(lds + OFF_V + d * VROW + pc * 16 + 8) = (v2u){R.v[i].z, R.v[i].w}; }
;     LAS f32x4* BT4 = (LAS f32x4*)(lds + OFF_B);
;     {   const f32x4* src = (const f32x4*)(F.ws + WS_BT4) + kvh * 4 * NBT;
; #pragma unroll
;         for (int i = 0; i < 3; ++i) BT4[tid + 512 * i] = src[tid + 512 * i]; }
;     __syncthreads();
; __device__ __forceinline__ void p2_mix(Frame& F, int slot) {
;     ...
;         if (F.tid == 0) F.MISC[16] = __hip_atomic_fetch_add(F.ctl + CW_ATTQ + 64 * F.dom, 1u, RLX_AGENT);
;         __syncthreads();
;         const int nid = (int)F.MISC[16];
;         if (nid < NU) att::attn_issue(F, base + nid, R);
.LBB0_545:
	s_lshl_b32 s2, s33, 2
	s_and_b32 s45, s2, 4
	s_add_i32 s54, s27, s45
	s_lshl_b32 s54, s54, 2
	s_load_dword s55, s[20:21], s54
	s_mul_i32 s2, s45, 0x1800
	s_add_u32 s2, s25, s2
	s_addc_u32 s3, s26, 0
	v_mov_b32_e32 v201, v2
	v_lshl_add_u64 v[8:9], s[2:3], 0, v[200:201]
	v_add_co_u32_e32 v8, vcc, 0x2000, v8
	global_load_dwordx4 v[4:7], v200, s[2:3]
	s_nop 0
	v_addc_co_u32_e32 v9, vcc, 0, v9, vcc
	global_load_dwordx4 v[8:11], v[8:9], off
	s_nop 0
	global_load_dwordx4 v[12:15], v242, s[2:3]
	s_waitcnt vmcnt(4)
	ds_write_b128 v230, v[114:117]
	ds_write_b128 v231, v[118:121]
	s_waitcnt vmcnt(3)
	ds_write_b128 v232, v[126:129]
	ds_write_b128 v233, v[122:125]
	ds_write_b128 v234, v[130:133]
	ds_write_b128 v235, v[134:137]
	ds_write2_b64 v236, v[138:139], v[140:141] offset1:1
	ds_write2_b64 v237, v[142:143], v[144:145] offset1:1
	ds_write2_b64 v238, v[146:147], v[148:149] offset1:1
	ds_write2_b64 v239, v[150:151], v[152:153] offset1:1
	ds_write2_b64 v240, v[154:155], v[156:157] offset1:1
	ds_write2_b64 v241, v[158:159], v[160:161] offset1:1
	s_waitcnt vmcnt(2)
	ds_write_b128 v218, v[4:7]
	s_waitcnt vmcnt(1)
	ds_write_b128 v219, v[8:11]
	s_waitcnt vmcnt(0)
	ds_write_b128 v220, v[12:15]
	s_waitcnt lgkmcnt(0)
	s_barrier
	s_add_i32 s44, s33, 0x80
	v_mov_b32_e32 v3, s44
	v_cmp_lt_i32_e64 s[2:3], s42, v3
	s_nop 1
	s_and_b64 vcc, exec, s[2:3]
	s_cbranch_vccnz .LBB0_574
	s_add_i32 s4, s44, s11
	s_ashr_i32 s23, s4, 5
	s_lshl_b32 s4, s4, 6
	s_and_b32 s22, s4, 0x780
	s_and_b32 s46, s4, 64
	s_addk_i32 s22, 0xff80
	s_lshl_b32 s47, s23, 11
	s_lshl_b32 s14, s46, 1
	s_cmpk_gt_u32 s22, 0x7ff
	v_lshl_add_u64 v[6:7], v[194:195], 0, s[14:15]
	s_cbranch_scc1 .LBB0_552
	v_or_b32_e32 v3, s22, v1
	v_or_b32_e32 v4, s47, v3
	v_ashrrev_i32_e32 v5, 31, v4
	v_lshlrev_b64 v[4:5], 8, v[4:5]
	v_lshl_add_u64 v[4:5], v[6:7], 0, v[4:5]
	global_load_dwordx4 v[114:117], v[4:5], off
	s_branch .LBB0_553
